# P1 epilogue stores write-through (sc1) to cut dirty-L2 writeback at the grid barrier
# baseline (speedup 1.0000x reference)
.LBB0_169:
	v_and_or_b32 v128, v128, 15, s89
	v_lshl_add_u32 v167, s18, 8, v128
	v_and_b32_e32 v128, 63, v168
	v_lshlrev_b32_e32 v140, 1, v128
	v_and_b32_e32 v170, 0xfcf, v167
	s_cmp_lg_u64 s[40:41], 0
	v_lshl_add_u64 v[156:157], s[40:41], 0, v[140:141]
	v_lshlrev_b32_e32 v140, 7, v170
	s_cselect_b64 s[74:75], -1, 0
	s_and_b32 s0, s18, -16
	v_lshl_add_u64 v[158:159], v[156:157], 0, v[140:141]
	v_ashrrev_i32_e32 v140, 6, v168
	s_cmp_eq_u64 s[40:41], 0
	v_cvt_pk_bf16_f32 v128, v124, v125
	v_cvt_pk_bf16_f32 v129, v126, v127
	v_cvt_pk_bf16_f32 v130, v120, v121
	v_cvt_pk_bf16_f32 v131, v122, v123
	v_add_u32_e32 v154, s0, v140
	s_cbranch_scc1 .LBB0_171
	v_ashrrev_i32_e32 v155, 31, v154
	v_lshlrev_b64 v[160:161], 19, v[154:155]
	v_lshl_add_u64 v[160:161], v[158:159], 0, v[160:161]
	s_mov_b64 s[40:41], 0
	global_store_dwordx4 v[160:161], v[128:131], off sc1
	s_branch .LBB0_172

.LBB0_172:
	v_mov_b64_e32 v[160:161], s[28:29]
	v_ashrrev_i32_e32 v151, 31, v150
	v_mad_i64_i32 v[160:161], s[14:15], v167, s95, v[160:161]
	s_andn2_b64 vcc, exec, s[40:41]
	v_lshl_add_u64 v[160:161], v[150:151], 1, v[160:161]
	s_cbranch_vccnz .LBB0_174
	global_store_dwordx4 v[160:161], v[128:131], off sc1
.LBB0_174:
	s_ashr_i32 s14, s18, 4
	s_lshl_b32 s1, s14, 11
	s_addk_i32 s1, 0xf800
	v_add_u32_e32 v128, s1, v170
	v_ashrrev_i32_e32 v129, 31, v128
	v_lshlrev_b64 v[128:129], 12, v[128:129]
	v_cmp_ne_u64_e64 s[40:41], 0, v[152:153]
	v_lshl_add_u64 v[128:129], v[152:153], 0, v[128:129]
	s_and_saveexec_b64 s[18:19], s[40:41]
	s_cbranch_execz .LBB0_176
	global_store_dwordx4 v[128:129], v[124:127], off sc1
	global_store_dwordx4 v[128:129], v[120:123], off offset:16 sc1
.LBB0_176:
	s_or_b64 exec, exec, s[18:19]
	v_cndmask_b32_e64 v124, 0, 1, s[74:75]
	v_cmp_ne_u32_e64 s[42:43], 1, v124
	v_add_u32_e32 v124, 0x80, v168
	v_cvt_pk_bf16_f32 v120, v116, v117
	v_cvt_pk_bf16_f32 v121, v118, v119
	v_cvt_pk_bf16_f32 v122, v112, v113
	v_cvt_pk_bf16_f32 v123, v114, v115
	s_andn2_b64 vcc, exec, s[74:75]
	v_ashrrev_i32_e32 v124, 6, v124
	s_cbranch_vccnz .LBB0_183
	v_add_u32_e32 v126, s0, v124
	v_ashrrev_i32_e32 v127, 31, v126
	v_lshlrev_b64 v[126:127], 19, v[126:127]
	v_lshl_add_u64 v[126:127], v[158:159], 0, v[126:127]
	global_store_dwordx4 v[126:127], v[120:123], off sc1
	s_cbranch_execnz .LBB0_179
.LBB0_178:
	global_store_dwordx4 v[160:161], v[120:123], off offset:256 sc1
.LBB0_179:
	s_and_saveexec_b64 s[18:19], s[40:41]
	s_cbranch_execz .LBB0_181
	global_store_dwordx4 v[128:129], v[116:119], off offset:512 sc1
	global_store_dwordx4 v[128:129], v[112:115], off offset:528 sc1
.LBB0_181:
	s_or_b64 exec, exec, s[18:19]
	s_movk_i32 s15, 0xfdf
	v_bitop3_b32 v120, v167, s15, 16 bitop3:0xc8
	v_lshlrev_b32_e32 v140, 7, v120
	v_lshl_add_u64 v[116:117], v[156:157], 0, v[140:141]
	v_cvt_pk_bf16_f32 v112, v108, v109
	v_cvt_pk_bf16_f32 v113, v110, v111
	v_cvt_pk_bf16_f32 v114, v104, v105
	s_and_b64 vcc, exec, s[42:43]
	v_cvt_pk_bf16_f32 v115, v106, v107
	s_cbranch_vccnz .LBB0_184
	v_ashrrev_i32_e32 v155, 31, v154
	v_lshlrev_b64 v[118:119], 19, v[154:155]
	v_lshl_add_u64 v[118:119], v[116:117], 0, v[118:119]
	s_mov_b64 s[18:19], 0
	global_store_dwordx4 v[118:119], v[112:115], off sc1
	s_branch .LBB0_185

.LBB0_185:
	v_or_b32_e32 v121, 16, v167
	v_mov_b64_e32 v[118:119], s[28:29]
	v_mad_i64_i32 v[118:119], s[16:17], v121, s95, v[118:119]
	s_andn2_b64 vcc, exec, s[18:19]
	v_lshl_add_u64 v[118:119], v[150:151], 1, v[118:119]
	s_cbranch_vccnz .LBB0_187
	global_store_dwordx4 v[118:119], v[112:115], off sc1
.LBB0_187:
	s_nop 1
	v_add_u32_e32 v112, s1, v120
	v_ashrrev_i32_e32 v113, 31, v112
	v_lshlrev_b64 v[112:113], 12, v[112:113]
	v_lshl_add_u64 v[112:113], v[152:153], 0, v[112:113]
	s_and_saveexec_b64 s[18:19], s[40:41]
	s_cbranch_execz .LBB0_189
	global_store_dwordx4 v[112:113], v[108:111], off sc1
	global_store_dwordx4 v[112:113], v[104:107], off offset:16 sc1
.LBB0_189:
	s_or_b64 exec, exec, s[18:19]
	s_nop 0
	v_cvt_pk_bf16_f32 v104, v100, v101
	v_cvt_pk_bf16_f32 v105, v102, v103
	v_cvt_pk_bf16_f32 v106, v96, v97
	s_and_b64 vcc, exec, s[42:43]
	v_cvt_pk_bf16_f32 v107, v98, v99
	s_cbranch_vccnz .LBB0_196
	v_add_u32_e32 v108, s0, v124
	v_ashrrev_i32_e32 v109, 31, v108
	v_lshlrev_b64 v[108:109], 19, v[108:109]
	v_lshl_add_u64 v[108:109], v[116:117], 0, v[108:109]
	global_store_dwordx4 v[108:109], v[104:107], off sc1
	s_cbranch_execnz .LBB0_192
.LBB0_191:
	global_store_dwordx4 v[118:119], v[104:107], off offset:256 sc1
.LBB0_192:
	s_and_saveexec_b64 s[18:19], s[40:41]
	s_cbranch_execz .LBB0_194
	global_store_dwordx4 v[112:113], v[100:103], off offset:512 sc1
	global_store_dwordx4 v[112:113], v[96:99], off offset:528 sc1
.LBB0_194:
	s_or_b64 exec, exec, s[18:19]
	s_movk_i32 s15, 0xfef
	v_bitop3_b32 v104, v167, s15, 32 bitop3:0xc8
	v_lshlrev_b32_e32 v140, 7, v104
	v_lshl_add_u64 v[100:101], v[156:157], 0, v[140:141]
	v_cvt_pk_bf16_f32 v96, v92, v93
	v_cvt_pk_bf16_f32 v97, v94, v95
	v_cvt_pk_bf16_f32 v98, v88, v89
	s_and_b64 vcc, exec, s[42:43]
	v_cvt_pk_bf16_f32 v99, v90, v91
	s_cbranch_vccnz .LBB0_197
	v_ashrrev_i32_e32 v155, 31, v154
	v_lshlrev_b64 v[102:103], 19, v[154:155]
	v_lshl_add_u64 v[102:103], v[100:101], 0, v[102:103]
	s_mov_b64 s[18:19], 0
	global_store_dwordx4 v[102:103], v[96:99], off sc1
	s_branch .LBB0_198

.LBB0_198:
	v_or_b32_e32 v105, 32, v167
	v_mov_b64_e32 v[102:103], s[28:29]
	v_mad_i64_i32 v[102:103], s[16:17], v105, s95, v[102:103]
	s_andn2_b64 vcc, exec, s[18:19]
	v_lshl_add_u64 v[102:103], v[150:151], 1, v[102:103]
	s_cbranch_vccnz .LBB0_200
	global_store_dwordx4 v[102:103], v[96:99], off sc1
.LBB0_200:
	s_nop 1
	v_add_u32_e32 v96, s1, v104
	v_ashrrev_i32_e32 v97, 31, v96
	v_lshlrev_b64 v[96:97], 12, v[96:97]
	v_lshl_add_u64 v[96:97], v[152:153], 0, v[96:97]
	s_and_saveexec_b64 s[18:19], s[40:41]
	s_cbranch_execz .LBB0_202
	global_store_dwordx4 v[96:97], v[92:95], off sc1
	global_store_dwordx4 v[96:97], v[88:91], off offset:16 sc1
.LBB0_202:
	s_or_b64 exec, exec, s[18:19]
	s_nop 0
	v_cvt_pk_bf16_f32 v88, v84, v85
	v_cvt_pk_bf16_f32 v89, v86, v87
	v_cvt_pk_bf16_f32 v90, v80, v81
	s_and_b64 vcc, exec, s[42:43]
	v_cvt_pk_bf16_f32 v91, v82, v83
	s_cbranch_vccnz .LBB0_209
	v_add_u32_e32 v92, s0, v124
	v_ashrrev_i32_e32 v93, 31, v92
	v_lshlrev_b64 v[92:93], 19, v[92:93]
	v_lshl_add_u64 v[92:93], v[100:101], 0, v[92:93]
	global_store_dwordx4 v[92:93], v[88:91], off sc1
	s_cbranch_execnz .LBB0_205
.LBB0_204:
	global_store_dwordx4 v[102:103], v[88:91], off offset:256 sc1
.LBB0_205:
	s_and_saveexec_b64 s[18:19], s[40:41]
	s_cbranch_execz .LBB0_207
	global_store_dwordx4 v[96:97], v[84:87], off offset:512 sc1
	global_store_dwordx4 v[96:97], v[80:83], off offset:528 sc1
.LBB0_207:
	s_or_b64 exec, exec, s[18:19]
	s_movk_i32 s15, 0xfff
	v_bitop3_b32 v88, v167, s15, 48 bitop3:0xc8
	v_lshlrev_b32_e32 v140, 7, v88
	v_lshl_add_u64 v[84:85], v[156:157], 0, v[140:141]
	v_cvt_pk_bf16_f32 v80, v76, v77
	v_cvt_pk_bf16_f32 v81, v78, v79
	v_cvt_pk_bf16_f32 v82, v72, v73
	s_and_b64 vcc, exec, s[42:43]
	v_cvt_pk_bf16_f32 v83, v74, v75
	s_cbranch_vccnz .LBB0_210
	v_ashrrev_i32_e32 v155, 31, v154
	v_lshlrev_b64 v[86:87], 19, v[154:155]
	v_lshl_add_u64 v[86:87], v[84:85], 0, v[86:87]
	s_mov_b64 s[18:19], 0
	global_store_dwordx4 v[86:87], v[80:83], off sc1
	s_branch .LBB0_211

.LBB0_211:
	v_or_b32_e32 v89, 48, v167
	v_mov_b64_e32 v[86:87], s[28:29]
	v_mad_i64_i32 v[86:87], s[16:17], v89, s95, v[86:87]
	s_andn2_b64 vcc, exec, s[18:19]
	v_lshl_add_u64 v[86:87], v[150:151], 1, v[86:87]
	s_cbranch_vccnz .LBB0_213
	global_store_dwordx4 v[86:87], v[80:83], off sc1
.LBB0_213:
	s_nop 1
	v_add_u32_e32 v80, s1, v88
	v_ashrrev_i32_e32 v81, 31, v80
	v_lshlrev_b64 v[80:81], 12, v[80:81]
	v_lshl_add_u64 v[80:81], v[152:153], 0, v[80:81]
	s_and_saveexec_b64 s[18:19], s[40:41]
	s_cbranch_execz .LBB0_215
	global_store_dwordx4 v[80:81], v[76:79], off sc1
	global_store_dwordx4 v[80:81], v[72:75], off offset:16 sc1
.LBB0_215:
	s_or_b64 exec, exec, s[18:19]
	s_mul_i32 s14, s14, 15
	s_addk_i32 s14, 0xf00f
	s_cmp_eq_u32 s12, 15
	v_add_u32_e32 v82, s14, v88
	s_cselect_b64 s[16:17], -1, 0
	s_cmp_eq_u32 s13, 16
	v_ashrrev_i32_e32 v83, 31, v82
	s_cselect_b64 s[12:13], -1, 0
	v_lshlrev_b64 v[82:83], 12, v[82:83]
	s_and_b64 s[18:19], s[16:17], s[12:13]
	v_cmp_lt_u32_e32 vcc, s96, v88
	v_lshl_add_u64 v[82:83], s[66:67], 0, v[82:83]
	s_and_b64 s[74:75], s[18:19], vcc
	v_lshl_add_u64 v[82:83], v[150:151], 2, v[82:83]
	s_and_saveexec_b64 s[76:77], s[74:75]
	s_cbranch_execz .LBB0_217
	v_add_co_u32_e32 v88, vcc, 0x603c000, v82
	s_nop 1
	v_addc_co_u32_e32 v89, vcc, 0, v83, vcc
	global_store_dwordx4 v[88:89], v[76:79], off sc1
	global_store_dwordx4 v[88:89], v[72:75], off offset:16 sc1
.LBB0_217:
	s_or_b64 exec, exec, s[76:77]
	s_nop 0
	v_cvt_pk_bf16_f32 v72, v68, v69
	v_cvt_pk_bf16_f32 v73, v70, v71
	v_cvt_pk_bf16_f32 v74, v64, v65
	s_and_b64 vcc, exec, s[42:43]
	v_cvt_pk_bf16_f32 v75, v66, v67
	s_cbranch_vccnz .LBB0_226
	v_add_u32_e32 v76, s0, v124
	v_ashrrev_i32_e32 v77, 31, v76
	v_lshlrev_b64 v[76:77], 19, v[76:77]
	v_lshl_add_u64 v[76:77], v[84:85], 0, v[76:77]
	global_store_dwordx4 v[76:77], v[72:75], off sc1
	s_cbranch_execnz .LBB0_220
.LBB0_219:
	global_store_dwordx4 v[86:87], v[72:75], off offset:256 sc1
.LBB0_220:
	s_and_saveexec_b64 s[76:77], s[40:41]
	s_cbranch_execz .LBB0_222
	global_store_dwordx4 v[80:81], v[68:71], off offset:512 sc1
	global_store_dwordx4 v[80:81], v[64:67], off offset:528 sc1
	s_or_b64 exec, exec, s[76:77]
	s_and_saveexec_b64 s[76:77], s[74:75]
	s_cbranch_execnz .LBB0_223
	s_branch .LBB0_224

.LBB0_223:
	v_add_co_u32_e32 v72, vcc, 0x603c000, v82
	s_nop 1
	v_addc_co_u32_e32 v73, vcc, 0, v83, vcc
	global_store_dwordx4 v[72:73], v[68:71], off offset:512 sc1
	global_store_dwordx4 v[72:73], v[64:67], off offset:528 sc1
.LBB0_224:
	s_or_b64 exec, exec, s[76:77]
	v_add_u32_e32 v70, 0x80, v167
	v_and_b32_e32 v72, 0xfcf, v70
	v_lshlrev_b32_e32 v140, 7, v72
	v_lshl_add_u64 v[68:69], v[156:157], 0, v[140:141]
	v_cvt_pk_bf16_f32 v64, v60, v61
	v_cvt_pk_bf16_f32 v65, v62, v63
	v_cvt_pk_bf16_f32 v66, v56, v57
	s_and_b64 vcc, exec, s[42:43]
	v_cvt_pk_bf16_f32 v67, v58, v59
	s_cbranch_vccnz .LBB0_227
	v_ashrrev_i32_e32 v155, 31, v154
	v_lshlrev_b64 v[74:75], 19, v[154:155]
	v_lshl_add_u64 v[74:75], v[68:69], 0, v[74:75]
	s_mov_b64 s[74:75], 0
	global_store_dwordx4 v[74:75], v[64:67], off sc1
	s_branch .LBB0_228

.LBB0_228:
	v_mov_b64_e32 v[74:75], s[28:29]
	v_mad_i64_i32 v[70:71], s[12:13], v70, s95, v[74:75]
	s_andn2_b64 vcc, exec, s[74:75]
	v_lshl_add_u64 v[70:71], v[150:151], 1, v[70:71]
	s_cbranch_vccnz .LBB0_230
	global_store_dwordx4 v[70:71], v[64:67], off sc1
.LBB0_230:
	s_nop 1
	v_add_u32_e32 v64, s1, v72
	v_ashrrev_i32_e32 v65, 31, v64
	v_lshlrev_b64 v[64:65], 12, v[64:65]
	v_lshl_add_u64 v[64:65], v[152:153], 0, v[64:65]
	s_and_saveexec_b64 s[74:75], s[40:41]
	s_cbranch_execz .LBB0_232
	global_store_dwordx4 v[64:65], v[60:63], off sc1
	global_store_dwordx4 v[64:65], v[56:59], off offset:16 sc1
.LBB0_232:
	s_or_b64 exec, exec, s[74:75]
	s_nop 0
	v_cvt_pk_bf16_f32 v56, v52, v53
	v_cvt_pk_bf16_f32 v57, v54, v55
	v_cvt_pk_bf16_f32 v58, v48, v49
	s_and_b64 vcc, exec, s[42:43]
	v_cvt_pk_bf16_f32 v59, v50, v51
	s_cbranch_vccnz .LBB0_239
	v_add_u32_e32 v60, s0, v124
	v_ashrrev_i32_e32 v61, 31, v60
	v_lshlrev_b64 v[60:61], 19, v[60:61]
	v_lshl_add_u64 v[60:61], v[68:69], 0, v[60:61]
	global_store_dwordx4 v[60:61], v[56:59], off sc1
	s_cbranch_execnz .LBB0_235
.LBB0_234:
	global_store_dwordx4 v[70:71], v[56:59], off offset:256 sc1
.LBB0_235:
	s_and_saveexec_b64 s[74:75], s[40:41]
	s_cbranch_execz .LBB0_237
	global_store_dwordx4 v[64:65], v[52:55], off offset:512 sc1
	global_store_dwordx4 v[64:65], v[48:51], off offset:528 sc1
.LBB0_237:
	s_or_b64 exec, exec, s[74:75]
	v_add_u32_e32 v54, 0x90, v167
	v_and_b32_e32 v56, 0xfdf, v54
	v_lshlrev_b32_e32 v140, 7, v56
	v_lshl_add_u64 v[52:53], v[156:157], 0, v[140:141]
	v_cvt_pk_bf16_f32 v48, v44, v45
	v_cvt_pk_bf16_f32 v49, v46, v47
	v_cvt_pk_bf16_f32 v50, v40, v41
	s_and_b64 vcc, exec, s[42:43]
	v_cvt_pk_bf16_f32 v51, v42, v43
	s_cbranch_vccnz .LBB0_240
	v_ashrrev_i32_e32 v155, 31, v154
	v_lshlrev_b64 v[58:59], 19, v[154:155]
	v_lshl_add_u64 v[58:59], v[52:53], 0, v[58:59]
	s_mov_b64 s[74:75], 0
	global_store_dwordx4 v[58:59], v[48:51], off sc1
	s_branch .LBB0_241

.LBB0_241:
	v_mov_b64_e32 v[58:59], s[28:29]
	v_mad_i64_i32 v[54:55], s[12:13], v54, s95, v[58:59]
	s_andn2_b64 vcc, exec, s[74:75]
	v_lshl_add_u64 v[54:55], v[150:151], 1, v[54:55]
	s_cbranch_vccnz .LBB0_243
	global_store_dwordx4 v[54:55], v[48:51], off sc1
.LBB0_243:
	s_nop 1
	v_add_u32_e32 v48, s1, v56
	v_ashrrev_i32_e32 v49, 31, v48
	v_lshlrev_b64 v[48:49], 12, v[48:49]
	v_lshl_add_u64 v[48:49], v[152:153], 0, v[48:49]
	s_and_saveexec_b64 s[74:75], s[40:41]
	s_cbranch_execz .LBB0_245
	global_store_dwordx4 v[48:49], v[44:47], off sc1
	global_store_dwordx4 v[48:49], v[40:43], off offset:16 sc1
.LBB0_245:
	s_or_b64 exec, exec, s[74:75]
	s_nop 0
	v_cvt_pk_bf16_f32 v40, v36, v37
	v_cvt_pk_bf16_f32 v41, v38, v39
	v_cvt_pk_bf16_f32 v42, v32, v33
	s_and_b64 vcc, exec, s[42:43]
	v_cvt_pk_bf16_f32 v43, v34, v35
	s_cbranch_vccnz .LBB0_252
	v_add_u32_e32 v44, s0, v124
	v_ashrrev_i32_e32 v45, 31, v44
	v_lshlrev_b64 v[44:45], 19, v[44:45]
	v_lshl_add_u64 v[44:45], v[52:53], 0, v[44:45]
	global_store_dwordx4 v[44:45], v[40:43], off sc1
	s_cbranch_execnz .LBB0_248
.LBB0_247:
	global_store_dwordx4 v[54:55], v[40:43], off offset:256 sc1
.LBB0_248:
	s_and_saveexec_b64 s[74:75], s[40:41]
	s_cbranch_execz .LBB0_250
	global_store_dwordx4 v[48:49], v[36:39], off offset:512 sc1
	global_store_dwordx4 v[48:49], v[32:35], off offset:528 sc1
.LBB0_250:
	s_or_b64 exec, exec, s[74:75]
	v_add_u32_e32 v38, 0xa0, v167
	v_and_b32_e32 v40, 0xfef, v38
	v_lshlrev_b32_e32 v140, 7, v40
	v_lshl_add_u64 v[36:37], v[156:157], 0, v[140:141]
	v_cvt_pk_bf16_f32 v32, v28, v29
	v_cvt_pk_bf16_f32 v33, v30, v31
	v_cvt_pk_bf16_f32 v34, v24, v25
	s_and_b64 vcc, exec, s[42:43]
	v_cvt_pk_bf16_f32 v35, v26, v27
	s_cbranch_vccnz .LBB0_253
	v_ashrrev_i32_e32 v155, 31, v154
	v_lshlrev_b64 v[42:43], 19, v[154:155]
	v_lshl_add_u64 v[42:43], v[36:37], 0, v[42:43]
	s_mov_b64 s[74:75], 0
	global_store_dwordx4 v[42:43], v[32:35], off sc1
	s_branch .LBB0_254

.LBB0_254:
	v_mov_b64_e32 v[42:43], s[28:29]
	v_mad_i64_i32 v[38:39], s[12:13], v38, s95, v[42:43]
	s_andn2_b64 vcc, exec, s[74:75]
	v_lshl_add_u64 v[38:39], v[150:151], 1, v[38:39]
	s_cbranch_vccnz .LBB0_256
	global_store_dwordx4 v[38:39], v[32:35], off sc1
.LBB0_256:
	s_nop 1
	v_add_u32_e32 v32, s1, v40
	v_ashrrev_i32_e32 v33, 31, v32
	v_lshlrev_b64 v[32:33], 12, v[32:33]
	v_lshl_add_u64 v[32:33], v[152:153], 0, v[32:33]
	s_and_saveexec_b64 s[74:75], s[40:41]
	s_cbranch_execz .LBB0_258
	global_store_dwordx4 v[32:33], v[28:31], off sc1
	global_store_dwordx4 v[32:33], v[24:27], off offset:16 sc1
.LBB0_258:
	s_or_b64 exec, exec, s[74:75]
	s_nop 0
	v_cvt_pk_bf16_f32 v24, v20, v21
	v_cvt_pk_bf16_f32 v25, v22, v23
	v_cvt_pk_bf16_f32 v26, v16, v17
	s_and_b64 vcc, exec, s[42:43]
	v_cvt_pk_bf16_f32 v27, v18, v19
	s_cbranch_vccnz .LBB0_265
	v_add_u32_e32 v28, s0, v124
	v_ashrrev_i32_e32 v29, 31, v28
	v_lshlrev_b64 v[28:29], 19, v[28:29]
	v_lshl_add_u64 v[28:29], v[36:37], 0, v[28:29]
	global_store_dwordx4 v[28:29], v[24:27], off sc1
	s_cbranch_execnz .LBB0_261
.LBB0_260:
	global_store_dwordx4 v[38:39], v[24:27], off offset:256 sc1
.LBB0_261:
	s_and_saveexec_b64 s[74:75], s[40:41]
	s_cbranch_execz .LBB0_263
	global_store_dwordx4 v[32:33], v[20:23], off offset:512 sc1
	global_store_dwordx4 v[32:33], v[16:19], off offset:528 sc1
.LBB0_263:
	s_or_b64 exec, exec, s[74:75]
	v_add_u32_e32 v22, 0xb0, v167
	v_and_b32_e32 v24, 0xfff, v22
	v_lshlrev_b32_e32 v140, 7, v24
	v_lshl_add_u64 v[20:21], v[156:157], 0, v[140:141]
	v_cvt_pk_bf16_f32 v16, v12, v13
	v_cvt_pk_bf16_f32 v17, v14, v15
	v_cvt_pk_bf16_f32 v18, v8, v9
	s_and_b64 vcc, exec, s[42:43]
	v_cvt_pk_bf16_f32 v19, v10, v11
	s_cbranch_vccnz .LBB0_266
	v_ashrrev_i32_e32 v155, 31, v154
	v_lshlrev_b64 v[26:27], 19, v[154:155]
	v_lshl_add_u64 v[26:27], v[20:21], 0, v[26:27]
	s_mov_b64 s[74:75], 0
	global_store_dwordx4 v[26:27], v[16:19], off sc1
	s_branch .LBB0_267

.LBB0_267:
	v_mov_b64_e32 v[26:27], s[28:29]
	v_mad_i64_i32 v[22:23], s[12:13], v22, s95, v[26:27]
	s_andn2_b64 vcc, exec, s[74:75]
	v_lshl_add_u64 v[22:23], v[150:151], 1, v[22:23]
	s_cbranch_vccnz .LBB0_269
	global_store_dwordx4 v[22:23], v[16:19], off sc1
.LBB0_269:
	s_nop 1
	v_add_u32_e32 v16, s1, v24
	v_ashrrev_i32_e32 v17, 31, v16
	v_lshlrev_b64 v[16:17], 12, v[16:17]
	v_lshl_add_u64 v[16:17], v[152:153], 0, v[16:17]
	s_and_saveexec_b64 s[74:75], s[40:41]
	s_cbranch_execz .LBB0_271
	global_store_dwordx4 v[16:17], v[12:15], off sc1
	global_store_dwordx4 v[16:17], v[8:11], off offset:16 sc1
.LBB0_271:
	s_or_b64 exec, exec, s[74:75]
	v_add_u32_e32 v18, s14, v24
	v_ashrrev_i32_e32 v19, 31, v18
	v_lshlrev_b64 v[18:19], 12, v[18:19]
	v_cmp_lt_u32_e32 vcc, s96, v24
	v_lshl_add_u64 v[18:19], s[66:67], 0, v[18:19]
	s_and_b64 s[18:19], s[18:19], vcc
	v_lshl_add_u64 v[18:19], v[150:151], 2, v[18:19]
	s_and_saveexec_b64 s[74:75], s[18:19]
	s_cbranch_execz .LBB0_273
	v_add_co_u32_e32 v24, vcc, 0x603c000, v18
	s_nop 1
	v_addc_co_u32_e32 v25, vcc, 0, v19, vcc
	global_store_dwordx4 v[24:25], v[12:15], off sc1
	global_store_dwordx4 v[24:25], v[8:11], off offset:16 sc1
.LBB0_273:
	s_or_b64 exec, exec, s[74:75]
	s_nop 0
	v_cvt_pk_bf16_f32 v8, v4, v5
	v_cvt_pk_bf16_f32 v9, v6, v7
	v_cvt_pk_bf16_f32 v10, v0, v1
	s_and_b64 vcc, exec, s[42:43]
	v_cvt_pk_bf16_f32 v11, v2, v3
	s_cbranch_vccnz .LBB0_283
	v_add_u32_e32 v12, s0, v124
	v_ashrrev_i32_e32 v13, 31, v12
	v_lshlrev_b64 v[12:13], 19, v[12:13]
	v_lshl_add_u64 v[12:13], v[20:21], 0, v[12:13]
	global_store_dwordx4 v[12:13], v[8:11], off sc1
	s_cbranch_execnz .LBB0_276
.LBB0_275:
	global_store_dwordx4 v[22:23], v[8:11], off offset:256 sc1
.LBB0_276:
	s_and_saveexec_b64 s[42:43], s[40:41]
	s_cbranch_execz .LBB0_279
	global_store_dwordx4 v[16:17], v[4:7], off offset:512 sc1
	global_store_dwordx4 v[16:17], v[0:3], off offset:528 sc1
	s_or_b64 exec, exec, s[42:43]
	s_and_saveexec_b64 s[40:41], s[18:19]
	s_cbranch_execnz .LBB0_280

.LBB0_280:
	v_add_co_u32_e32 v8, vcc, 0x603c000, v18
	s_nop 1
	v_addc_co_u32_e32 v9, vcc, 0, v19, vcc
	global_store_dwordx4 v[8:9], v[4:7], off offset:512 sc1
	global_store_dwordx4 v[8:9], v[0:3], off offset:528 sc1
	s_or_b64 exec, exec, s[40:41]
	s_andn2_b64 vcc, exec, s[38:39]
	s_mov_b64 s[18:19], -1
	s_cbranch_vccnz .LBB0_145
